# GEMM unit loop: first K iteration peeled, each accumulator's first MFMA takes C=0, the 128 per-unit zeroing moves removed
# speedup vs baseline: 1.0059x; 1.0059x over previous
; #define PG8_STAGE(bufoff, gbase, voff) do { _Pragma("unroll") for (int _i = 0; _i < 2; ++_i) \
;         __builtin_amdgcn_global_load_lds((const unsigned*)((const char*)(gbase) + (voff)[_i]), (LAS unsigned*)(lds + (bufoff) + ldsw + _i * 8192), 16, 0, 0); } while (0)
; #define PG8_LDA(dst, b, h) do { _Pragma("unroll") for (int m = 0; m < 4; ++m) _Pragma("unroll") for (int k = 0; k < 2; ++k) dst[m][k] = *(const LAS bf16x8*)(lds + PG8_SA(b, h) + aoff + m * 2048 + k * 1024); } while (0)
; #define PG8_LDB(dst, b, h) do { _Pragma("unroll") for (int n = 0; n < 2; ++n) _Pragma("unroll") for (int k = 0; k < 2; ++k) dst[n][k] = *(const LAS bf16x8*)(lds + PG8_SB(b, h) + boff + n * 2048 + k * 1024); } while (0)
; #define PG8_MMA(ai, bj, At, Bt) do { __builtin_amdgcn_s_setprio(1); _Pragma("unroll") for (int m = 0; m < 4; ++m) _Pragma("unroll") for (int n = 0; n < 2; ++n) _Pragma("unroll") for (int k = 0; k < 2; ++k) \
;         acc[ai][bj][m][n] = __builtin_amdgcn_mfma_f32_16x16x32_bf16(Bt[n][k], At[m][k], acc[ai][bj][m][n], 0, 0, 0); __builtin_amdgcn_s_setprio(0); } while (0)
; #define PG8_BAR __builtin_amdgcn_s_barrier()
; DI void gemm_phase(LAS unsigned char* lds, const GemmD g, const int kind, const int l) {
;     ...
;     f32x4 acc[2][2][4][2];
; #pragma unroll
;     for (int a = 0; a < 2; ++a)
; #pragma unroll
;         for (int b = 0; b < 2; ++b)
; #pragma unroll
;             for (int m = 0; m < 4; ++m)
; #pragma unroll
;                 for (int n = 0; n < 2; ++n) acc[a][b][m][n] = (f32x4){0.f, 0.f, 0.f, 0.f};
;     ...
;         for (int t = 0; t < nt; t += 2) {
;             const bool last = (t == nt - 2);
;             const char* a1 = cA + (size_t)(t + 1) * kstep;
;             const char* a2 = last ? nA : cA + (size_t)(t + 2) * kstep; const char* b2 = last ? nB : cB + (size_t)(t + 2) * kstep;
;             const char* a3 = a2 + kstep; const char* b3 = b2 + kstep;
;             PG8_LDB(B0, 0, 0); PG8_LDB(B1, 0, 1); PG8_SCHED; PG8_LDA(At, 0, 0); PG8_STAGE(PG8_SA(1, 1), a1 + hstepA, voffA);
;             PG8_WAIT_V(8); PG8_WAIT_L(0); PG8_BAR; PG8_MMA(0, 0, At, B0); PG8_MMA(0, 1, At, B1); PG8_BAR; PG8_SCHED;
;             PG8_LDA(At, 0, 1); PG8_STAGE(PG8_SB(0, 0), b2, voffB); PG8_STAGE(PG8_SB(0, 1), b2 + hstepB, voffB); PG8_STAGE(PG8_SA(0, 0), a2, voffA);
;             PG8_WAIT_V(8); PG8_WAIT_L(0); PG8_BAR; PG8_MMA(1, 0, At, B0); PG8_MMA(1, 1, At, B1); PG8_BAR; PG8_SCHED;
.LBB0_253:
	s_add_u32 s4, s4, 0x80
	s_addc_u32 s5, s5, 0
	s_add_u32 s8, s6, 0x100
	s_addc_u32 s9, s7, 0
	s_mov_b32 s6, 0
	v_readlane_b32 s10, v255, 46
	v_readlane_b32 s11, v255, 47
	s_nop 3
	s_cmp_eq_u64 s[10:11], 0
	s_cbranch_scc0 .Lprio_done
	s_setprio 1
.Lprio_done:
	s_add_i32 s10, s6, 2
	s_add_u32 s11, s4, 0x80
	s_addc_u32 s7, s5, 0
	s_add_i32 s14, 0, 0x10000
	s_cmp_eq_u32 s50, s6
	s_cselect_b32 s7, s75, s7
	s_cselect_b32 s6, s74, s11
	v_add_u32_e32 v24, s14, v214
	s_cselect_b32 s13, s77, s9
	s_cselect_b32 s12, s76, s8
	s_add_i32 s11, 0, 0x14000
	ds_read_b128 v[130:133], v24
	ds_read_b128 v[134:137], v24 offset:1024
	ds_read_b128 v[138:141], v24 offset:2048
	ds_read_b128 v[142:145], v24 offset:3072
	v_add_u32_e32 v24, s11, v214
	ds_read_b128 v[146:149], v24
	ds_read_b128 v[150:153], v24 offset:1024
	ds_read_b128 v[154:157], v24 offset:2048
	ds_read_b128 v[172:175], v24 offset:3072
	v_lshl_add_u64 v[240:241], s[4:5], 0, v[168:169]
	s_add_i32 m0, s67, 0xc000
	ds_read_b128 v[176:179], v215
	ds_read_b128 v[180:183], v215 offset:1024
	ds_read_b128 v[216:219], v215 offset:2048
	ds_read_b128 v[220:223], v215 offset:3072
	ds_read_b128 v[224:227], v215 offset:4096
	ds_read_b128 v[228:231], v215 offset:5120
	ds_read_b128 v[232:235], v215 offset:6144
	ds_read_b128 v[236:239], v215 offset:7168
	global_load_lds_dwordx4 v[240:241], off
	v_lshl_add_u64 v[240:241], s[4:5], 0, v[170:171]
	s_add_i32 m0, s67, 0xe000
	s_nop 0
	global_load_lds_dwordx4 v[240:241], off
	s_waitcnt vmcnt(8)
	s_waitcnt lgkmcnt(0)
	s_barrier
	s_waitcnt lgkmcnt(0)
	v_mfma_f32_16x16x32_bf16 v[126:129], v[130:133], v[176:179], 0
	v_mfma_f32_16x16x32_bf16 v[122:125], v[138:141], v[176:179], 0
	v_mfma_f32_16x16x32_bf16 v[110:113], v[130:133], v[216:219], 0
	v_mfma_f32_16x16x32_bf16 v[106:109], v[138:141], v[216:219], 0
	v_mfma_f32_16x16x32_bf16 v[94:97], v[130:133], v[224:227], 0
	v_mfma_f32_16x16x32_bf16 v[90:93], v[138:141], v[224:227], 0
	v_mfma_f32_16x16x32_bf16 v[78:81], v[130:133], v[232:235], 0
	v_mfma_f32_16x16x32_bf16 v[74:77], v[138:141], v[232:235], 0
	v_mfma_f32_16x16x32_bf16 v[126:129], v[134:137], v[180:183], v[126:129]
	v_mfma_f32_16x16x32_bf16 v[122:125], v[142:145], v[180:183], v[122:125]
	v_mfma_f32_16x16x32_bf16 v[110:113], v[134:137], v[220:223], v[110:113]
	v_mfma_f32_16x16x32_bf16 v[106:109], v[142:145], v[220:223], v[106:109]
	v_mfma_f32_16x16x32_bf16 v[94:97], v[134:137], v[228:231], v[94:97]
	v_mfma_f32_16x16x32_bf16 v[90:93], v[142:145], v[228:231], v[90:93]
	v_mfma_f32_16x16x32_bf16 v[78:81], v[134:137], v[236:239], v[78:81]
	v_mfma_f32_16x16x32_bf16 v[74:77], v[142:145], v[236:239], v[74:77]
	v_mfma_f32_16x16x32_bf16 v[118:121], v[146:149], v[176:179], 0
	v_mfma_f32_16x16x32_bf16 v[114:117], v[154:157], v[176:179], 0
	v_mfma_f32_16x16x32_bf16 v[102:105], v[146:149], v[216:219], 0
	v_mfma_f32_16x16x32_bf16 v[98:101], v[154:157], v[216:219], 0
	v_mfma_f32_16x16x32_bf16 v[86:89], v[146:149], v[224:227], 0
	v_mfma_f32_16x16x32_bf16 v[82:85], v[154:157], v[224:227], 0
	v_mfma_f32_16x16x32_bf16 v[70:73], v[146:149], v[232:235], 0
	v_mfma_f32_16x16x32_bf16 v[66:69], v[154:157], v[232:235], 0
	v_mfma_f32_16x16x32_bf16 v[118:121], v[150:153], v[180:183], v[118:121]
	v_mfma_f32_16x16x32_bf16 v[114:117], v[172:175], v[180:183], v[114:117]
	v_mfma_f32_16x16x32_bf16 v[102:105], v[150:153], v[220:223], v[102:105]
	v_mfma_f32_16x16x32_bf16 v[98:101], v[172:175], v[220:223], v[98:101]
	v_mfma_f32_16x16x32_bf16 v[86:89], v[150:153], v[228:231], v[86:89]
	v_mfma_f32_16x16x32_bf16 v[82:85], v[172:175], v[228:231], v[82:85]
	v_mfma_f32_16x16x32_bf16 v[70:73], v[150:153], v[236:239], v[70:73]
	v_mfma_f32_16x16x32_bf16 v[66:69], v[172:175], v[236:239], v[66:69]
	s_barrier
	s_add_i32 s14, s14, s66
	v_lshl_add_u64 v[240:241], s[12:13], 0, v[160:161]
	s_mov_b32 m0, s14
	ds_read_b128 v[176:179], v215 offset:16384
	ds_read_b128 v[180:183], v215 offset:17408
	ds_read_b128 v[216:219], v215 offset:18432
	ds_read_b128 v[220:223], v215 offset:19456
	ds_read_b128 v[224:227], v215 offset:20480
	ds_read_b128 v[228:231], v215 offset:21504
	ds_read_b128 v[232:235], v215 offset:22528
	ds_read_b128 v[236:239], v215 offset:23552
	global_load_lds_dwordx4 v[240:241], off
	s_add_i32 m0, s14, 0x2000
	v_lshl_add_u64 v[242:243], s[12:13], 0, v[164:165]
	s_add_u32 s12, s12, s54
	s_addc_u32 s13, s13, s55
	s_add_i32 s11, s11, s66
	global_load_lds_dwordx4 v[242:243], off
	v_lshl_add_u64 v[244:245], s[12:13], 0, v[160:161]
	s_mov_b32 m0, s11
	v_lshl_add_u64 v[246:247], s[12:13], 0, v[164:165]
	global_load_lds_dwordx4 v[244:245], off
	s_add_i32 m0, s11, 0x2000
	v_lshl_add_u64 v[248:249], s[6:7], 0, v[158:159]
	global_load_lds_dwordx4 v[246:247], off
	s_mov_b32 m0, s67
	v_lshl_add_u64 v[250:251], s[6:7], 0, v[162:163]
	global_load_lds_dwordx4 v[248:249], off
	s_mov_b32 m0, s25
	s_nop 0
	global_load_lds_dwordx4 v[250:251], off
	s_waitcnt vmcnt(8)
	s_waitcnt lgkmcnt(0)
	s_barrier
; #define PG8_STAGE(bufoff, gbase, voff) do { _Pragma("unroll") for (int _i = 0; _i < 2; ++_i) \
;         __builtin_amdgcn_global_load_lds((const unsigned*)((const char*)(gbase) + (voff)[_i]), (LAS unsigned*)(lds + (bufoff) + ldsw + _i * 8192), 16, 0, 0); } while (0)
; #define PG8_LDA(dst, b, h) do { _Pragma("unroll") for (int m = 0; m < 4; ++m) _Pragma("unroll") for (int k = 0; k < 2; ++k) dst[m][k] = *(const LAS bf16x8*)(lds + PG8_SA(b, h) + aoff + m * 2048 + k * 1024); } while (0)
; #define PG8_LDB(dst, b, h) do { _Pragma("unroll") for (int n = 0; n < 2; ++n) _Pragma("unroll") for (int k = 0; k < 2; ++k) dst[n][k] = *(const LAS bf16x8*)(lds + PG8_SB(b, h) + boff + n * 2048 + k * 1024); } while (0)
; #define PG8_MMA(ai, bj, At, Bt) do { __builtin_amdgcn_s_setprio(1); _Pragma("unroll") for (int m = 0; m < 4; ++m) _Pragma("unroll") for (int n = 0; n < 2; ++n) _Pragma("unroll") for (int k = 0; k < 2; ++k) \
;         acc[ai][bj][m][n] = __builtin_amdgcn_mfma_f32_16x16x32_bf16(Bt[n][k], At[m][k], acc[ai][bj][m][n], 0, 0, 0); __builtin_amdgcn_s_setprio(0); } while (0)
; #define PG8_WAIT_V(n) asm volatile("s_waitcnt vmcnt(" #n ")" ::: "memory")
; #define PG8_WAIT_L(n) asm volatile("s_waitcnt lgkmcnt(" #n ")" ::: "memory")
; #define PG8_BAR __builtin_amdgcn_s_barrier()
; #define PG8_SCHED __builtin_amdgcn_sched_barrier(0)
; DI void gemm_phase(LAS unsigned char* lds, const GemmD g, const int kind, const int l) {
;     ...
;             PG8_WAIT_V(8); PG8_WAIT_L(0); PG8_BAR; PG8_MMA(1, 0, At, B0); PG8_MMA(1, 1, At, B1); PG8_BAR; PG8_SCHED;
;             PG8_LDB(B0, 1, 0); PG8_LDB(B1, 1, 1); PG8_SCHED; PG8_LDA(At, 1, 0); PG8_STAGE(PG8_SA(0, 1), a2 + hstepA, voffA);
;             PG8_WAIT_V(8); PG8_WAIT_L(0); PG8_BAR; PG8_MMA(0, 0, At, B0); PG8_MMA(0, 1, At, B1); PG8_BAR; PG8_SCHED;
	s_waitcnt lgkmcnt(0)
	v_mfma_f32_16x16x32_bf16 v[62:65], v[130:133], v[176:179], 0
	v_mfma_f32_16x16x32_bf16 v[58:61], v[138:141], v[176:179], 0
	v_mfma_f32_16x16x32_bf16 v[46:49], v[130:133], v[216:219], 0
	v_mfma_f32_16x16x32_bf16 v[42:45], v[138:141], v[216:219], 0
	v_mfma_f32_16x16x32_bf16 v[30:33], v[130:133], v[224:227], 0
	v_mfma_f32_16x16x32_bf16 v[26:29], v[138:141], v[224:227], 0
	v_mfma_f32_16x16x32_bf16 v[12:15], v[130:133], v[232:235], 0
	v_mfma_f32_16x16x32_bf16 v[8:11], v[138:141], v[232:235], 0
	v_mfma_f32_16x16x32_bf16 v[62:65], v[134:137], v[180:183], v[62:65]
	v_mfma_f32_16x16x32_bf16 v[58:61], v[142:145], v[180:183], v[58:61]
	v_mfma_f32_16x16x32_bf16 v[46:49], v[134:137], v[220:223], v[46:49]
	v_mfma_f32_16x16x32_bf16 v[42:45], v[142:145], v[220:223], v[42:45]
	v_mfma_f32_16x16x32_bf16 v[30:33], v[134:137], v[228:231], v[30:33]
	v_mfma_f32_16x16x32_bf16 v[26:29], v[142:145], v[228:231], v[26:29]
	v_mfma_f32_16x16x32_bf16 v[12:15], v[134:137], v[236:239], v[12:15]
	v_mfma_f32_16x16x32_bf16 v[8:11], v[142:145], v[236:239], v[8:11]
	v_mfma_f32_16x16x32_bf16 v[54:57], v[146:149], v[176:179], 0
	v_mfma_f32_16x16x32_bf16 v[50:53], v[154:157], v[176:179], 0
	v_mfma_f32_16x16x32_bf16 v[38:41], v[146:149], v[216:219], 0
	v_mfma_f32_16x16x32_bf16 v[34:37], v[154:157], v[216:219], 0
	v_mfma_f32_16x16x32_bf16 v[20:23], v[146:149], v[224:227], 0
	v_mfma_f32_16x16x32_bf16 v[16:19], v[154:157], v[224:227], 0
	v_mfma_f32_16x16x32_bf16 v[4:7], v[146:149], v[232:235], 0
	v_mfma_f32_16x16x32_bf16 v[0:3], v[154:157], v[232:235], 0
	v_mfma_f32_16x16x32_bf16 v[54:57], v[150:153], v[180:183], v[54:57]
	v_mfma_f32_16x16x32_bf16 v[50:53], v[172:175], v[180:183], v[50:53]
	v_mfma_f32_16x16x32_bf16 v[38:41], v[150:153], v[220:223], v[38:41]
	v_mfma_f32_16x16x32_bf16 v[34:37], v[172:175], v[220:223], v[34:37]
	v_mfma_f32_16x16x32_bf16 v[20:23], v[150:153], v[228:231], v[20:23]
	v_mfma_f32_16x16x32_bf16 v[16:19], v[172:175], v[228:231], v[16:19]
	v_mfma_f32_16x16x32_bf16 v[4:7], v[150:153], v[236:239], v[4:7]
	v_mfma_f32_16x16x32_bf16 v[0:3], v[172:175], v[236:239], v[0:3]
	s_barrier
	s_add_i32 s11, 0, 0x18000
	v_add_u32_e32 v24, s11, v214
	s_add_i32 s12, 0, 0x1c000
	ds_read_b128 v[130:133], v24
	ds_read_b128 v[134:137], v24 offset:1024
	ds_read_b128 v[138:141], v24 offset:2048
	ds_read_b128 v[142:145], v24 offset:3072
	v_add_u32_e32 v24, s12, v214
	ds_read_b128 v[146:149], v24
	ds_read_b128 v[150:153], v24 offset:1024
	ds_read_b128 v[154:157], v24 offset:2048
	ds_read_b128 v[172:175], v24 offset:3072
	s_add_u32 s6, s6, s52
	s_addc_u32 s7, s7, s53
	s_mov_b32 m0, s60
	v_lshl_add_u64 v[252:253], s[6:7], 0, v[158:159]
	ds_read_b128 v[176:179], v215 offset:32768
	ds_read_b128 v[180:183], v215 offset:33792
	ds_read_b128 v[216:219], v215 offset:34816
	ds_read_b128 v[220:223], v215 offset:35840
	ds_read_b128 v[224:227], v215 offset:36864
	ds_read_b128 v[228:231], v215 offset:37888
	ds_read_b128 v[232:235], v215 offset:38912
	ds_read_b128 v[236:239], v215 offset:39936
	global_load_lds_dwordx4 v[252:253], off
	v_lshl_add_u64 v[252:253], s[6:7], 0, v[162:163]
	s_mov_b32 m0, s61
	s_nop 0
	global_load_lds_dwordx4 v[252:253], off
	s_waitcnt vmcnt(8)
	s_waitcnt lgkmcnt(0)
	s_barrier
	s_waitcnt lgkmcnt(0)
	v_mfma_f32_16x16x32_bf16 v[126:129], v[130:133], v[176:179], v[126:129]
	v_mfma_f32_16x16x32_bf16 v[122:125], v[138:141], v[176:179], v[122:125]
	v_mfma_f32_16x16x32_bf16 v[110:113], v[130:133], v[216:219], v[110:113]
	v_mfma_f32_16x16x32_bf16 v[106:109], v[138:141], v[216:219], v[106:109]
	v_mfma_f32_16x16x32_bf16 v[94:97], v[130:133], v[224:227], v[94:97]
	v_mfma_f32_16x16x32_bf16 v[90:93], v[138:141], v[224:227], v[90:93]
	v_mfma_f32_16x16x32_bf16 v[78:81], v[130:133], v[232:235], v[78:81]
	v_mfma_f32_16x16x32_bf16 v[74:77], v[138:141], v[232:235], v[74:77]
	v_mfma_f32_16x16x32_bf16 v[126:129], v[134:137], v[180:183], v[126:129]
	v_mfma_f32_16x16x32_bf16 v[122:125], v[142:145], v[180:183], v[122:125]
	v_mfma_f32_16x16x32_bf16 v[110:113], v[134:137], v[220:223], v[110:113]
	v_mfma_f32_16x16x32_bf16 v[106:109], v[142:145], v[220:223], v[106:109]
	v_mfma_f32_16x16x32_bf16 v[94:97], v[134:137], v[228:231], v[94:97]
	v_mfma_f32_16x16x32_bf16 v[90:93], v[142:145], v[228:231], v[90:93]
	v_mfma_f32_16x16x32_bf16 v[78:81], v[134:137], v[236:239], v[78:81]
	v_mfma_f32_16x16x32_bf16 v[74:77], v[142:145], v[236:239], v[74:77]
	v_mfma_f32_16x16x32_bf16 v[118:121], v[146:149], v[176:179], v[118:121]
	v_mfma_f32_16x16x32_bf16 v[114:117], v[154:157], v[176:179], v[114:117]
	v_mfma_f32_16x16x32_bf16 v[102:105], v[146:149], v[216:219], v[102:105]
	v_mfma_f32_16x16x32_bf16 v[98:101], v[154:157], v[216:219], v[98:101]
	v_mfma_f32_16x16x32_bf16 v[86:89], v[146:149], v[224:227], v[86:89]
	v_mfma_f32_16x16x32_bf16 v[82:85], v[154:157], v[224:227], v[82:85]
	v_mfma_f32_16x16x32_bf16 v[70:73], v[146:149], v[232:235], v[70:73]
	v_mfma_f32_16x16x32_bf16 v[66:69], v[154:157], v[232:235], v[66:69]
	v_mfma_f32_16x16x32_bf16 v[118:121], v[150:153], v[180:183], v[118:121]
	v_mfma_f32_16x16x32_bf16 v[114:117], v[172:175], v[180:183], v[114:117]
	v_mfma_f32_16x16x32_bf16 v[102:105], v[150:153], v[220:223], v[102:105]
	v_mfma_f32_16x16x32_bf16 v[98:101], v[172:175], v[220:223], v[98:101]
	v_mfma_f32_16x16x32_bf16 v[86:89], v[150:153], v[228:231], v[86:89]
	v_mfma_f32_16x16x32_bf16 v[82:85], v[172:175], v[228:231], v[82:85]
	v_mfma_f32_16x16x32_bf16 v[70:73], v[150:153], v[236:239], v[70:73]
	v_mfma_f32_16x16x32_bf16 v[66:69], v[172:175], v[236:239], v[66:69]
	s_barrier
; #define PG8_STAGE(bufoff, gbase, voff) do { _Pragma("unroll") for (int _i = 0; _i < 2; ++_i) \
;         __builtin_amdgcn_global_load_lds((const unsigned*)((const char*)(gbase) + (voff)[_i]), (LAS unsigned*)(lds + (bufoff) + ldsw + _i * 8192), 16, 0, 0); } while (0)
; #define PG8_LDA(dst, b, h) do { _Pragma("unroll") for (int m = 0; m < 4; ++m) _Pragma("unroll") for (int k = 0; k < 2; ++k) dst[m][k] = *(const LAS bf16x8*)(lds + PG8_SA(b, h) + aoff + m * 2048 + k * 1024); } while (0)
; #define PG8_MMA(ai, bj, At, Bt) do { __builtin_amdgcn_s_setprio(1); _Pragma("unroll") for (int m = 0; m < 4; ++m) _Pragma("unroll") for (int n = 0; n < 2; ++n) _Pragma("unroll") for (int k = 0; k < 2; ++k) \
;         acc[ai][bj][m][n] = __builtin_amdgcn_mfma_f32_16x16x32_bf16(Bt[n][k], At[m][k], acc[ai][bj][m][n], 0, 0, 0); __builtin_amdgcn_s_setprio(0); } while (0)
; #define PG8_WAIT_V(n) asm volatile("s_waitcnt vmcnt(" #n ")" ::: "memory")
; #define PG8_WAIT_L(n) asm volatile("s_waitcnt lgkmcnt(" #n ")" ::: "memory")
; #define PG8_BAR __builtin_amdgcn_s_barrier()
; #define PG8_SCHED __builtin_amdgcn_sched_barrier(0)
; DI void gemm_phase(LAS unsigned char* lds, const GemmD g, const int kind, const int l) {
;     ...
;             PG8_LDA(At, 1, 1); PG8_STAGE(PG8_SB(1, 0), b3, voffB); PG8_STAGE(PG8_SB(1, 1), b3 + hstepB, voffB); PG8_STAGE(PG8_SA(1, 0), a3, voffA);
;             PG8_WAIT_V(8); PG8_WAIT_L(0); PG8_BAR; PG8_MMA(1, 0, At, B0); PG8_MMA(1, 1, At, B1); PG8_BAR; PG8_SCHED;
;         }
	s_add_i32 s6, s11, s66
	v_lshl_add_u64 v[240:241], v[240:241], 0, s[80:81]
	s_mov_b32 m0, s6
	ds_read_b128 v[176:179], v215 offset:49152
	ds_read_b128 v[180:183], v215 offset:50176
	ds_read_b128 v[216:219], v215 offset:51200
	ds_read_b128 v[220:223], v215 offset:52224
	ds_read_b128 v[224:227], v215 offset:53248
	ds_read_b128 v[228:231], v215 offset:54272
	ds_read_b128 v[232:235], v215 offset:55296
	ds_read_b128 v[236:239], v215 offset:56320
	global_load_lds_dwordx4 v[240:241], off
	v_lshl_add_u64 v[240:241], v[242:243], 0, s[80:81]
	s_add_i32 m0, s6, 0x2000
	s_add_i32 s6, s12, s66
	global_load_lds_dwordx4 v[240:241], off
	v_lshl_add_u64 v[240:241], v[244:245], 0, s[80:81]
	s_mov_b32 m0, s6
	s_nop 0
	global_load_lds_dwordx4 v[240:241], off
	v_lshl_add_u64 v[240:241], v[246:247], 0, s[80:81]
	s_add_i32 m0, s6, 0x2000
	s_nop 0
	global_load_lds_dwordx4 v[240:241], off
	v_lshl_add_u64 v[240:241], v[248:249], 0, s[80:81]
	s_mov_b32 m0, s2
	s_nop 0
	global_load_lds_dwordx4 v[240:241], off
	v_lshl_add_u64 v[240:241], v[250:251], 0, s[80:81]
	s_mov_b32 m0, s82
	s_nop 0
	global_load_lds_dwordx4 v[240:241], off
	s_waitcnt vmcnt(8)
	s_waitcnt lgkmcnt(0)
	s_barrier
	s_waitcnt lgkmcnt(0)
	v_mfma_f32_16x16x32_bf16 v[62:65], v[130:133], v[176:179], v[62:65]
	v_mfma_f32_16x16x32_bf16 v[58:61], v[138:141], v[176:179], v[58:61]
	v_mfma_f32_16x16x32_bf16 v[46:49], v[130:133], v[216:219], v[46:49]
	v_mfma_f32_16x16x32_bf16 v[42:45], v[138:141], v[216:219], v[42:45]
	v_mfma_f32_16x16x32_bf16 v[30:33], v[130:133], v[224:227], v[30:33]
	v_mfma_f32_16x16x32_bf16 v[26:29], v[138:141], v[224:227], v[26:29]
	v_mfma_f32_16x16x32_bf16 v[12:15], v[130:133], v[232:235], v[12:15]
	v_mfma_f32_16x16x32_bf16 v[8:11], v[138:141], v[232:235], v[8:11]
	v_mfma_f32_16x16x32_bf16 v[62:65], v[134:137], v[180:183], v[62:65]
	v_mfma_f32_16x16x32_bf16 v[58:61], v[142:145], v[180:183], v[58:61]
	v_mfma_f32_16x16x32_bf16 v[46:49], v[134:137], v[220:223], v[46:49]
	v_mfma_f32_16x16x32_bf16 v[42:45], v[142:145], v[220:223], v[42:45]
	v_mfma_f32_16x16x32_bf16 v[30:33], v[134:137], v[228:231], v[30:33]
	v_mfma_f32_16x16x32_bf16 v[26:29], v[142:145], v[228:231], v[26:29]
	v_mfma_f32_16x16x32_bf16 v[12:15], v[134:137], v[236:239], v[12:15]
	v_mfma_f32_16x16x32_bf16 v[8:11], v[142:145], v[236:239], v[8:11]
	v_mfma_f32_16x16x32_bf16 v[54:57], v[146:149], v[176:179], v[54:57]
	v_mfma_f32_16x16x32_bf16 v[50:53], v[154:157], v[176:179], v[50:53]
	v_mfma_f32_16x16x32_bf16 v[38:41], v[146:149], v[216:219], v[38:41]
	v_mfma_f32_16x16x32_bf16 v[34:37], v[154:157], v[216:219], v[34:37]
	v_mfma_f32_16x16x32_bf16 v[20:23], v[146:149], v[224:227], v[20:23]
	v_mfma_f32_16x16x32_bf16 v[16:19], v[154:157], v[224:227], v[16:19]
	v_mfma_f32_16x16x32_bf16 v[4:7], v[146:149], v[232:235], v[4:7]
	v_mfma_f32_16x16x32_bf16 v[0:3], v[154:157], v[232:235], v[0:3]
	v_mfma_f32_16x16x32_bf16 v[54:57], v[150:153], v[180:183], v[54:57]
	v_mfma_f32_16x16x32_bf16 v[50:53], v[172:175], v[180:183], v[50:53]
	v_mfma_f32_16x16x32_bf16 v[38:41], v[150:153], v[220:223], v[38:41]
	v_mfma_f32_16x16x32_bf16 v[34:37], v[172:175], v[220:223], v[34:37]
	v_mfma_f32_16x16x32_bf16 v[20:23], v[150:153], v[228:231], v[20:23]
	v_mfma_f32_16x16x32_bf16 v[16:19], v[172:175], v[228:231], v[16:19]
	v_mfma_f32_16x16x32_bf16 v[4:7], v[150:153], v[236:239], v[4:7]
	v_mfma_f32_16x16x32_bf16 v[0:3], v[172:175], v[236:239], v[0:3]
	s_barrier
	s_add_u32 s4, s4, 0x100
	s_addc_u32 s5, s5, 0
	s_add_u32 s8, s8, 0x100
	s_addc_u32 s9, s9, 0
	s_cmp_ge_u32 s10, s83
	s_mov_b32 s6, s10
	s_cbranch_scc0 .LBB0_254
	s_branch .Lkl_done

; #define PG8_MMA(ai, bj, At, Bt) do { __builtin_amdgcn_s_setprio(1); _Pragma("unroll") for (int m = 0; m < 4; ++m) _Pragma("unroll") for (int n = 0; n < 2; ++n) _Pragma("unroll") for (int k = 0; k < 2; ++k) \
;         acc[ai][bj][m][n] = __builtin_amdgcn_mfma_f32_16x16x32_bf16(Bt[n][k], At[m][k], acc[ai][bj][m][n], 0, 0, 0); __builtin_amdgcn_s_setprio(0); } while (0)
; #define PG8_WAIT_V(n) asm volatile("s_waitcnt vmcnt(" #n ")" ::: "memory")
; #define PG8_WAIT_L(n) asm volatile("s_waitcnt lgkmcnt(" #n ")" ::: "memory")
; #define PG8_BAR __builtin_amdgcn_s_barrier()
; #define PG8_SCHED __builtin_amdgcn_sched_barrier(0)
; DI void gemm_phase(LAS unsigned char* lds, const GemmD g, const int kind, const int l) {
;     ...
;             PG8_WAIT_V(8); PG8_WAIT_L(0); PG8_BAR; PG8_MMA(1, 0, At, B0); PG8_MMA(1, 1, At, B1); PG8_BAR; PG8_SCHED;
;         }
;         if (wr == 0) PG8_BAR;
;         epilogue(kind, l, acc, cur, wr, wc, fr, fq);
.Lkl_done:
	s_setprio 0
	v_readlane_b32 s4, v255, 46
	v_readlane_b32 s5, v255, 47
	s_and_b64 vcc, exec, s[4:5]
	s_cbranch_vccz .LBB0_257
	s_barrier
